# final-norm phase: rss loads hoisted with the row loads, per-row vmcnt(0) store drains removed (on top of v38)
# speedup vs baseline: 1.0178x; 1.0140x over previous
.LBB0_85:
	s_ashr_i32 s1, s0, 31
	s_add_i32 s8, s0, 1
	s_lshl_b64 s[2:3], s[0:1], 11
	s_ashr_i32 s9, s8, 31
	s_add_i32 s4, s0, 2
	s_waitcnt vmcnt(0)
	v_lshl_add_u64 v[0:1], v[40:41], 0, s[2:3]
	s_lshl_b64 s[2:3], s[8:9], 11
	s_ashr_i32 s5, s4, 31
	global_load_dwordx4 v[46:49], v[0:1], off
	global_load_dwordx4 v[50:53], v[0:1], off offset:1024
	v_lshl_add_u64 v[0:1], v[40:41], 0, s[2:3]
	s_lshl_b64 s[2:3], s[4:5], 11
	global_load_dwordx4 v[36:39], v[0:1], off
	global_load_dwordx4 v[32:35], v[0:1], off offset:1024
	v_lshl_add_u64 v[0:1], v[40:41], 0, s[2:3]
	s_add_i32 s2, s0, 3
	s_ashr_i32 s3, s2, 31
	s_lshl_b64 s[10:11], s[2:3], 11
	global_load_dwordx4 v[28:31], v[0:1], off
	global_load_dwordx4 v[24:27], v[0:1], off offset:1024
	v_lshl_add_u64 v[0:1], v[40:41], 0, s[10:11]
	s_lshl_b64 s[10:11], s[0:1], 2
	s_add_u32 s10, s18, s10
	s_addc_u32 s11, s19, s11
	global_load_dwordx4 v[20:23], v[0:1], off
	global_load_dwordx4 v[4:7], v[0:1], off offset:1024
	global_load_dwordx4 v[12:15], v[42:43], off offset:16
	global_load_dwordx4 v[16:19], v[42:43], off
	s_nop 0
	global_load_dwordx4 v[0:3], v[42:43], off offset:2064
	global_load_dwordx4 v[8:11], v[42:43], off offset:2048
	global_load_dword v54, v153, s[10:11]
	global_load_dword v62, v153, s[10:11] offset:4
	global_load_dword v63, v153, s[10:11] offset:8
	global_load_dword v64, v153, s[10:11] offset:12
	s_lshl_b64 s[10:11], s[0:1], 12
	s_waitcnt vmcnt(0)
	v_lshlrev_b32_e32 v56, 16, v46
	v_and_b32_e32 v57, 0xffff0000, v46
	v_lshlrev_b32_e32 v46, 16, v47
	v_and_b32_e32 v47, 0xffff0000, v47
	v_lshlrev_b32_e32 v58, 16, v48
	v_and_b32_e32 v59, 0xffff0000, v48
	v_lshlrev_b32_e32 v60, 16, v49
	v_and_b32_e32 v61, 0xffff0000, v49
	s_waitcnt vmcnt(0)
	v_fmamk_f32 v54, v54, 0x3a800000, v214
	v_cmp_gt_f32_e32 vcc, s25, v54
	v_mul_f32_e32 v55, 0x4b800000, v54
	s_nop 0
	v_cndmask_b32_e32 v54, v54, v55, vcc
	v_rsq_f32_e32 v54, v54
	s_nop 0
	v_mul_f32_e32 v55, 0x45800000, v54
	v_cndmask_b32_e32 v54, v54, v55, vcc
	v_pk_mul_f32 v[56:57], v[54:55], v[56:57] op_sel_hi:[0,1]
	v_pk_mul_f32 v[46:47], v[54:55], v[46:47] op_sel_hi:[0,1]
	v_pk_mul_f32 v[48:49], v[18:19], v[46:47]
	v_pk_mul_f32 v[46:47], v[16:17], v[56:57]
	v_lshl_add_u64 v[56:57], v[44:45], 0, s[10:11]
	global_store_dwordx4 v[56:57], v[46:49], off
	s_lshl_b64 s[10:11], s[8:9], 2
	s_add_u32 s10, s18, s10
	v_pk_mul_f32 v[46:47], v[54:55], v[58:59] op_sel_hi:[0,1]
	v_pk_mul_f32 v[48:49], v[54:55], v[60:61] op_sel_hi:[0,1]
	v_pk_mul_f32 v[48:49], v[14:15], v[48:49]
	v_pk_mul_f32 v[46:47], v[12:13], v[46:47]
	global_store_dwordx4 v[56:57], v[46:49], off offset:16
	s_addc_u32 s11, s19, s11
	s_lshl_b64 s[8:9], s[8:9], 12
	v_lshlrev_b32_e32 v46, 16, v50
	v_and_b32_e32 v47, 0xffff0000, v50
	v_lshlrev_b32_e32 v48, 16, v51
	v_and_b32_e32 v49, 0xffff0000, v51
	v_pk_mul_f32 v[46:47], v[54:55], v[46:47] op_sel_hi:[0,1]
	v_pk_mul_f32 v[48:49], v[54:55], v[48:49] op_sel_hi:[0,1]
	v_lshlrev_b32_e32 v50, 16, v52
	v_and_b32_e32 v51, 0xffff0000, v52
	v_lshlrev_b32_e32 v52, 16, v53
	v_and_b32_e32 v53, 0xffff0000, v53
	v_pk_mul_f32 v[48:49], v[10:11], v[48:49]
	v_pk_mul_f32 v[46:47], v[8:9], v[46:47]
	global_store_dwordx4 v[56:57], v[46:49], off offset:2048
	s_nop 1
	v_pk_mul_f32 v[46:47], v[54:55], v[50:51] op_sel_hi:[0,1]
	v_pk_mul_f32 v[48:49], v[54:55], v[52:53] op_sel_hi:[0,1]
	v_pk_mul_f32 v[48:49], v[2:3], v[48:49]
	v_pk_mul_f32 v[46:47], v[0:1], v[46:47]
	global_store_dwordx4 v[56:57], v[46:49], off offset:2064
	s_nop 1
	v_mov_b32_e32 v46, v62
	v_lshlrev_b32_e32 v50, 16, v38
	v_lshlrev_b32_e32 v48, 16, v36
	v_and_b32_e32 v49, 0xffff0000, v36
	v_lshlrev_b32_e32 v36, 16, v37
	v_and_b32_e32 v37, 0xffff0000, v37
	v_and_b32_e32 v51, 0xffff0000, v38
	v_lshlrev_b32_e32 v52, 16, v39
	v_and_b32_e32 v53, 0xffff0000, v39
	v_fmamk_f32 v46, v46, 0x3a800000, v214
	v_cmp_gt_f32_e32 vcc, s25, v46
	v_mul_f32_e32 v47, 0x4b800000, v46
	s_nop 0
	v_cndmask_b32_e32 v46, v46, v47, vcc
	v_rsq_f32_e32 v46, v46
	s_nop 0
	v_mul_f32_e32 v47, 0x45800000, v46
	v_cndmask_b32_e32 v46, v46, v47, vcc
	v_pk_mul_f32 v[48:49], v[46:47], v[48:49] op_sel_hi:[0,1]
	v_pk_mul_f32 v[36:37], v[46:47], v[36:37] op_sel_hi:[0,1]
	v_pk_mul_f32 v[38:39], v[18:19], v[36:37]
	v_pk_mul_f32 v[36:37], v[16:17], v[48:49]
	v_lshl_add_u64 v[48:49], v[44:45], 0, s[8:9]
	global_store_dwordx4 v[48:49], v[36:39], off
	s_lshl_b64 s[8:9], s[4:5], 2
	s_add_u32 s8, s18, s8
	v_pk_mul_f32 v[36:37], v[46:47], v[50:51] op_sel_hi:[0,1]
	v_pk_mul_f32 v[38:39], v[46:47], v[52:53] op_sel_hi:[0,1]
	v_pk_mul_f32 v[38:39], v[14:15], v[38:39]
	v_pk_mul_f32 v[36:37], v[12:13], v[36:37]
	global_store_dwordx4 v[48:49], v[36:39], off offset:16
	v_lshlrev_b32_e32 v50, 16, v35
	v_and_b32_e32 v51, 0xffff0000, v35
	v_lshlrev_b32_e32 v36, 16, v32
	v_and_b32_e32 v37, 0xffff0000, v32
	v_lshlrev_b32_e32 v32, 16, v33
	v_and_b32_e32 v33, 0xffff0000, v33
	v_pk_mul_f32 v[36:37], v[46:47], v[36:37] op_sel_hi:[0,1]
	v_pk_mul_f32 v[32:33], v[46:47], v[32:33] op_sel_hi:[0,1]
	v_lshlrev_b32_e32 v38, 16, v34
	v_and_b32_e32 v39, 0xffff0000, v34
	v_pk_mul_f32 v[34:35], v[10:11], v[32:33]
	v_pk_mul_f32 v[32:33], v[8:9], v[36:37]
	global_store_dwordx4 v[48:49], v[32:35], off offset:2048
	s_addc_u32 s9, s19, s9
	s_lshl_b64 s[4:5], s[4:5], 12
	v_pk_mul_f32 v[32:33], v[46:47], v[38:39] op_sel_hi:[0,1]
	v_pk_mul_f32 v[34:35], v[46:47], v[50:51] op_sel_hi:[0,1]
	v_pk_mul_f32 v[34:35], v[2:3], v[34:35]
	v_pk_mul_f32 v[32:33], v[0:1], v[32:33]
	global_store_dwordx4 v[48:49], v[32:35], off offset:2064
	s_nop 1
	v_mov_b32_e32 v32, v63
	v_lshlrev_b32_e32 v36, 16, v30
	v_lshlrev_b32_e32 v34, 16, v28
	v_and_b32_e32 v35, 0xffff0000, v28
	v_lshlrev_b32_e32 v28, 16, v29
	v_and_b32_e32 v29, 0xffff0000, v29
	v_and_b32_e32 v37, 0xffff0000, v30
	v_lshlrev_b32_e32 v38, 16, v31
	v_and_b32_e32 v39, 0xffff0000, v31
	v_fmamk_f32 v32, v32, 0x3a800000, v214
	v_cmp_gt_f32_e32 vcc, s25, v32
	v_mul_f32_e32 v33, 0x4b800000, v32
	s_nop 0
	v_cndmask_b32_e32 v32, v32, v33, vcc
	v_rsq_f32_e32 v32, v32
	s_nop 0
	v_mul_f32_e32 v33, 0x45800000, v32
	v_cndmask_b32_e32 v32, v32, v33, vcc
	v_pk_mul_f32 v[34:35], v[32:33], v[34:35] op_sel_hi:[0,1]
	v_pk_mul_f32 v[28:29], v[32:33], v[28:29] op_sel_hi:[0,1]
	v_pk_mul_f32 v[30:31], v[18:19], v[28:29]
	v_pk_mul_f32 v[28:29], v[16:17], v[34:35]
	v_lshl_add_u64 v[34:35], v[44:45], 0, s[4:5]
	global_store_dwordx4 v[34:35], v[28:31], off
	s_lshl_b64 s[4:5], s[2:3], 2
	s_add_u32 s4, s18, s4
	v_pk_mul_f32 v[28:29], v[32:33], v[36:37] op_sel_hi:[0,1]
	v_pk_mul_f32 v[30:31], v[32:33], v[38:39] op_sel_hi:[0,1]
	v_pk_mul_f32 v[30:31], v[14:15], v[30:31]
	v_pk_mul_f32 v[28:29], v[12:13], v[28:29]
	global_store_dwordx4 v[34:35], v[28:31], off offset:16
	v_lshlrev_b32_e32 v36, 16, v27
	v_and_b32_e32 v37, 0xffff0000, v27
	v_lshlrev_b32_e32 v28, 16, v24
	v_and_b32_e32 v29, 0xffff0000, v24
	v_lshlrev_b32_e32 v24, 16, v25
	v_and_b32_e32 v25, 0xffff0000, v25
	v_pk_mul_f32 v[28:29], v[32:33], v[28:29] op_sel_hi:[0,1]
	v_pk_mul_f32 v[24:25], v[32:33], v[24:25] op_sel_hi:[0,1]
	v_lshlrev_b32_e32 v30, 16, v26
	v_and_b32_e32 v31, 0xffff0000, v26
	v_pk_mul_f32 v[26:27], v[10:11], v[24:25]
	v_pk_mul_f32 v[24:25], v[8:9], v[28:29]
	global_store_dwordx4 v[34:35], v[24:27], off offset:2048
	s_addc_u32 s5, s19, s5
	s_lshl_b64 s[2:3], s[2:3], 12
	v_pk_mul_f32 v[24:25], v[32:33], v[30:31] op_sel_hi:[0,1]
	v_pk_mul_f32 v[26:27], v[32:33], v[36:37] op_sel_hi:[0,1]
	v_pk_mul_f32 v[26:27], v[2:3], v[26:27]
	v_pk_mul_f32 v[24:25], v[0:1], v[24:25]
	global_store_dwordx4 v[34:35], v[24:27], off offset:2064
	s_nop 1
	v_mov_b32_e32 v24, v64
	v_lshlrev_b32_e32 v28, 16, v22
	v_lshlrev_b32_e32 v26, 16, v20
	v_and_b32_e32 v27, 0xffff0000, v20
	v_lshlrev_b32_e32 v20, 16, v21
	v_and_b32_e32 v21, 0xffff0000, v21
	v_and_b32_e32 v29, 0xffff0000, v22
	v_lshlrev_b32_e32 v22, 16, v23
	v_and_b32_e32 v23, 0xffff0000, v23
	s_add_i32 s13, s13, s29
	s_add_i32 s0, s0, s24
	s_cmpk_gt_i32 s13, 0x1fff
	v_fmamk_f32 v24, v24, 0x3a800000, v214
	v_cmp_gt_f32_e32 vcc, s25, v24
	v_mul_f32_e32 v25, 0x4b800000, v24
	s_nop 0
	v_cndmask_b32_e32 v24, v24, v25, vcc
	v_rsq_f32_e32 v24, v24
	s_nop 0
	v_mul_f32_e32 v25, 0x45800000, v24
	v_cndmask_b32_e32 v24, v24, v25, vcc
	v_pk_mul_f32 v[26:27], v[24:25], v[26:27] op_sel_hi:[0,1]
	v_pk_mul_f32 v[20:21], v[24:25], v[20:21] op_sel_hi:[0,1]
	v_pk_mul_f32 v[18:19], v[18:19], v[20:21]
	v_pk_mul_f32 v[16:17], v[16:17], v[26:27]
	v_lshl_add_u64 v[20:21], v[44:45], 0, s[2:3]
	global_store_dwordx4 v[20:21], v[16:19], off
	s_nop 1
	v_pk_mul_f32 v[16:17], v[24:25], v[28:29] op_sel_hi:[0,1]
	v_pk_mul_f32 v[18:19], v[24:25], v[22:23] op_sel_hi:[0,1]
	v_pk_mul_f32 v[14:15], v[14:15], v[18:19]
	v_pk_mul_f32 v[12:13], v[12:13], v[16:17]
	global_store_dwordx4 v[20:21], v[12:15], off offset:16
	v_lshlrev_b32_e32 v16, 16, v7
	v_and_b32_e32 v17, 0xffff0000, v7
	v_lshlrev_b32_e32 v12, 16, v4
	v_and_b32_e32 v13, 0xffff0000, v4
	v_lshlrev_b32_e32 v4, 16, v5
	v_and_b32_e32 v5, 0xffff0000, v5
	v_pk_mul_f32 v[12:13], v[24:25], v[12:13] op_sel_hi:[0,1]
	v_pk_mul_f32 v[4:5], v[24:25], v[4:5] op_sel_hi:[0,1]
	v_lshlrev_b32_e32 v14, 16, v6
	v_and_b32_e32 v15, 0xffff0000, v6
	v_pk_mul_f32 v[6:7], v[10:11], v[4:5]
	v_pk_mul_f32 v[4:5], v[8:9], v[12:13]
	global_store_dwordx4 v[20:21], v[4:7], off offset:2048
	s_nop 1
	v_pk_mul_f32 v[4:5], v[24:25], v[14:15] op_sel_hi:[0,1]
	v_pk_mul_f32 v[6:7], v[24:25], v[16:17] op_sel_hi:[0,1]
	v_pk_mul_f32 v[2:3], v[2:3], v[6:7]
	v_pk_mul_f32 v[0:1], v[0:1], v[4:5]
	global_store_dwordx4 v[20:21], v[0:3], off offset:2064
	s_cbranch_scc0 .LBB0_85
